# v73 plus the two mixer1 load overlaps (LN loads before the statistics step; gate operands before the MFMA loop)
# speedup vs baseline: 1.0039x; 1.0039x over previous
; __device__ __forceinline__ unsigned pk2(float lo, float hi) { return pg8::cvt_pk_bf16(lo, hi); }
; __device__ __forceinline__ void phase_mixer1(const Params& p, LAS unsigned char* lds) {
;     ...
;                     const int t = 16 * wave + 4 * ps + sub; const float mean = stats[2 * t], rstd = stats[2 * t + 1];
;                     float x[8]; unpack8(*(const v4u*)(Z + (row0 + t) * NZ1 + 1024 + g * 128 + c8), x);
; #pragma unroll
;                     for (int q = 0; q < 8; ++q) { const float vn = (x[q] - mean) * rstd * g8[q] + b8[q]; vnT[vnt_off(c8 + q, t)] = (unsigned short)(pk2(vn, 0.f) & 0xffffu); }
;                 }
;             }
.LBB0_878:
	s_or_b64 exec, exec, s[86:87]
	s_waitcnt lgkmcnt(0)
	s_barrier
	v_lshl_add_u64 v[8:9], s[0:1], 0, v[120:121]
	ds_read_b64 v[6:7], v197
	v_mad_u64_u32 v[10:11], s[16:17], v8, s65, v[0:1]
	v_mov_b32_e32 v8, v11
	v_mad_u64_u32 v[8:9], s[16:17], v9, s65, v[8:9]
	v_mov_b32_e32 v11, v8
	v_lshl_add_u64 v[8:9], v[10:11], 0, s[40:41]
	v_lshl_add_u64 v[8:9], v[8:9], 0, v[138:139]
	s_andn2_b64 vcc, exec, s[18:19]
	s_waitcnt vmcnt(7)
	v_lshlrev_b32_e32 v10, 16, v2
	v_and_b32_e32 v2, 0xffff0000, v2
	v_lshlrev_b32_e32 v11, 16, v3
	v_and_b32_e32 v3, 0xffff0000, v3
	v_lshlrev_b32_e32 v12, 16, v4
	v_and_b32_e32 v4, 0xffff0000, v4
	v_lshlrev_b32_e32 v13, 16, v5
	v_and_b32_e32 v5, 0xffff0000, v5
	s_waitcnt lgkmcnt(0)
	v_sub_f32_e32 v10, v10, v6
	v_sub_f32_e32 v2, v2, v6
	v_sub_f32_e32 v11, v11, v6
	v_sub_f32_e32 v3, v3, v6
	v_sub_f32_e32 v12, v12, v6
	v_sub_f32_e32 v4, v4, v6
	v_sub_f32_e32 v13, v13, v6
	v_sub_f32_e32 v5, v5, v6
	v_mul_f32_e32 v6, v7, v10
	v_mul_f32_e32 v2, v7, v2
	s_waitcnt vmcnt(5)
	v_fma_f32 v6, v36, v6, v28
	v_fma_f32 v2, v37, v2, v29
	v_mul_f32_e32 v10, v7, v11
	v_cvt_pk_bf16_f32 v6, v6, v79
	ds_write_b16 v147, v6 offset:1024
	v_cvt_pk_bf16_f32 v2, v2, v79
	v_mul_f32_e32 v3, v7, v3
	v_mul_f32_e32 v11, v7, v12
	v_mul_f32_e32 v4, v7, v4
	v_mul_f32_e32 v12, v7, v13
	v_mul_f32_e32 v5, v7, v5
	v_fma_f32 v7, v38, v10, v30
	ds_write_b16 v148, v2 offset:1024
	v_cvt_pk_bf16_f32 v2, v7, v79
	v_fma_f32 v3, v39, v3, v31
	ds_write_b16 v149, v2 offset:1024
	v_cvt_pk_bf16_f32 v2, v3, v79
	s_waitcnt vmcnt(3)
	v_fma_f32 v10, v32, v11, v24
	ds_write_b16 v150, v2 offset:1024
	v_cvt_pk_bf16_f32 v2, v10, v79
	v_fma_f32 v4, v33, v4, v25
	ds_write_b16 v151, v2 offset:1024
	v_cvt_pk_bf16_f32 v2, v4, v79
	v_fma_f32 v11, v34, v12, v26
	v_fma_f32 v5, v35, v5, v27
	ds_write_b16 v152, v2 offset:1024
	v_cvt_pk_bf16_f32 v2, v11, v79
	ds_write_b16 v153, v2 offset:1024
	v_cvt_pk_bf16_f32 v10, v5, v79
	v_lshl_add_u64 v[6:7], s[0:1], 0, v[122:123]
	v_mad_u64_u32 v[8:9], s[16:17], v6, s65, v[0:1]
	v_mov_b32_e32 v6, v9
	v_mad_u64_u32 v[6:7], s[16:17], v7, s65, v[6:7]
	v_mov_b32_e32 v9, v6
	v_lshl_add_u64 v[6:7], v[8:9], 0, s[40:41]
	ds_read_b64 v[8:9], v198
	ds_write_b16 v154, v10 offset:1024
	v_lshl_add_u64 v[6:7], v[6:7], 0, v[138:139]
	s_waitcnt vmcnt(2)
	v_mov_b32_e32 v2, v226
	v_mov_b32_e32 v3, v227
	v_mov_b32_e32 v4, v228
	v_mov_b32_e32 v5, v229
	v_lshlrev_b32_e32 v10, 16, v2
	v_and_b32_e32 v2, 0xffff0000, v2
	v_lshlrev_b32_e32 v11, 16, v3
	v_and_b32_e32 v3, 0xffff0000, v3
	v_lshlrev_b32_e32 v12, 16, v4
	v_and_b32_e32 v4, 0xffff0000, v4
	v_lshlrev_b32_e32 v13, 16, v5
	v_and_b32_e32 v5, 0xffff0000, v5
	s_waitcnt lgkmcnt(1)
	v_sub_f32_e32 v10, v10, v8
	v_sub_f32_e32 v2, v2, v8
	v_sub_f32_e32 v11, v11, v8
	v_sub_f32_e32 v3, v3, v8
	v_sub_f32_e32 v12, v12, v8
	v_sub_f32_e32 v4, v4, v8
	v_sub_f32_e32 v13, v13, v8
	v_sub_f32_e32 v5, v5, v8
	v_mul_f32_e32 v8, v9, v10
	v_mul_f32_e32 v2, v9, v2
	v_fma_f32 v8, v36, v8, v28
	v_fma_f32 v2, v37, v2, v29
	v_mul_f32_e32 v10, v9, v11
	v_cvt_pk_bf16_f32 v8, v8, v79
	ds_write_b16 v155, v8 offset:1024
	v_cvt_pk_bf16_f32 v2, v2, v79
	v_mul_f32_e32 v3, v9, v3
	v_mul_f32_e32 v11, v9, v12
	v_mul_f32_e32 v4, v9, v4
	v_mul_f32_e32 v12, v9, v13
	v_mul_f32_e32 v5, v9, v5
	v_fma_f32 v9, v38, v10, v30
	ds_write_b16 v156, v2 offset:1024
	v_cvt_pk_bf16_f32 v2, v9, v79
	v_fma_f32 v3, v39, v3, v31
	ds_write_b16 v157, v2 offset:1024
	v_cvt_pk_bf16_f32 v2, v3, v79
	v_fma_f32 v10, v32, v11, v24
	ds_write_b16 v158, v2 offset:1024
	v_cvt_pk_bf16_f32 v2, v10, v79
	v_fma_f32 v4, v33, v4, v25
	ds_write_b16 v159, v2 offset:1024
	v_cvt_pk_bf16_f32 v2, v4, v79
	v_fma_f32 v11, v34, v12, v26
	v_fma_f32 v5, v35, v5, v27
	ds_write_b16 v160, v2 offset:1024
	v_cvt_pk_bf16_f32 v2, v11, v79
	ds_write_b16 v161, v2 offset:1024
	v_cvt_pk_bf16_f32 v8, v5, v79
	v_lshl_add_u64 v[6:7], s[0:1], 0, v[124:125]
	v_mad_u64_u32 v[0:1], s[16:17], v6, s65, v[0:1]
	v_mov_b32_e32 v6, v1
	v_mad_u64_u32 v[6:7], s[16:17], v7, s65, v[6:7]
	v_mov_b32_e32 v1, v6
	ds_read_b64 v[6:7], v199
	ds_write_b16 v162, v8 offset:1024
	v_lshl_add_u64 v[0:1], v[0:1], 0, s[40:41]
	v_lshl_add_u64 v[0:1], v[0:1], 0, v[138:139]
	s_waitcnt vmcnt(1)
	v_mov_b32_e32 v2, v230
	v_mov_b32_e32 v3, v231
	v_mov_b32_e32 v4, v232
	v_mov_b32_e32 v5, v233
	v_lshlrev_b32_e32 v8, 16, v2
	v_and_b32_e32 v2, 0xffff0000, v2
	v_lshlrev_b32_e32 v9, 16, v3
	v_and_b32_e32 v3, 0xffff0000, v3
	v_lshlrev_b32_e32 v10, 16, v4
	v_and_b32_e32 v4, 0xffff0000, v4
	v_lshlrev_b32_e32 v11, 16, v5
	v_and_b32_e32 v5, 0xffff0000, v5
	s_waitcnt lgkmcnt(1)
; __device__ __forceinline__ unsigned pk2(float lo, float hi) { return pg8::cvt_pk_bf16(lo, hi); }
; __device__ __forceinline__ void phase_mixer1(const Params& p, LAS unsigned char* lds) {
;     ...
;                     float x[8]; unpack8(*(const v4u*)(Z + (row0 + t) * NZ1 + 1024 + g * 128 + c8), x);
; #pragma unroll
;                     for (int q = 0; q < 8; ++q) { const float vn = (x[q] - mean) * rstd * g8[q] + b8[q]; vnT[vnt_off(c8 + q, t)] = (unsigned short)(pk2(vn, 0.f) & 0xffffu); }
;     ...
;                 const float bs = sgb[g * 128 + t];
; #pragma unroll
;                 for (int n = 0; n < 8; ++n) {
;                     const int col = g * 128 + n * 16 + 4 * fq; const v2u uw = *(const v2u*)(Z + (row0 + t) * NZ1 + 512 + col);
	v_sub_f32_e32 v8, v8, v6
	v_sub_f32_e32 v2, v2, v6
	v_sub_f32_e32 v9, v9, v6
	v_sub_f32_e32 v3, v3, v6
	v_sub_f32_e32 v10, v10, v6
	v_sub_f32_e32 v4, v4, v6
	v_sub_f32_e32 v11, v11, v6
	v_sub_f32_e32 v5, v5, v6
	v_mul_f32_e32 v6, v7, v8
	v_mul_f32_e32 v2, v7, v2
	v_fma_f32 v6, v36, v6, v28
	v_fma_f32 v2, v37, v2, v29
	v_mul_f32_e32 v8, v7, v9
	v_cvt_pk_bf16_f32 v6, v6, v79
	ds_write_b16 v163, v6 offset:1024
	v_cvt_pk_bf16_f32 v2, v2, v79
	v_mul_f32_e32 v3, v7, v3
	v_mul_f32_e32 v9, v7, v10
	v_mul_f32_e32 v4, v7, v4
	v_mul_f32_e32 v10, v7, v11
	v_mul_f32_e32 v5, v7, v5
	v_fma_f32 v7, v38, v8, v30
	ds_write_b16 v164, v2 offset:1024
	v_cvt_pk_bf16_f32 v2, v7, v79
	v_fma_f32 v3, v39, v3, v31
	ds_write_b16 v165, v2 offset:1024
	v_cvt_pk_bf16_f32 v2, v3, v79
	v_fma_f32 v8, v32, v9, v24
	ds_write_b16 v166, v2 offset:1024
	v_cvt_pk_bf16_f32 v2, v8, v79
	v_fma_f32 v4, v33, v4, v25
	ds_write_b16 v167, v2 offset:1024
	v_cvt_pk_bf16_f32 v2, v4, v79
	v_fma_f32 v9, v34, v10, v26
	v_fma_f32 v5, v35, v5, v27
	ds_write_b16 v168, v2 offset:1024
	v_cvt_pk_bf16_f32 v2, v9, v79
	ds_write_b16 v169, v2 offset:1024
	v_cvt_pk_bf16_f32 v44, v5, v79
	ds_read_b64 v[52:53], v200
	ds_write_b16 v170, v44 offset:1024
	v_mov_b32_e32 v3, 0
	v_mov_b32_e32 v2, v3
	v_mov_b32_e32 v1, v3
	v_mov_b32_e32 v0, v3
	v_mov_b32_e32 v7, v3
	v_mov_b32_e32 v6, v3
	v_mov_b32_e32 v5, v3
	v_mov_b32_e32 v4, v3
	v_mov_b32_e32 v11, v3
	v_mov_b32_e32 v10, v3
	v_mov_b32_e32 v9, v3
	v_mov_b32_e32 v8, v3
	v_mov_b32_e32 v15, v3
	v_mov_b32_e32 v14, v3
	v_mov_b32_e32 v13, v3
	v_mov_b32_e32 v12, v3
	v_mov_b32_e32 v19, v3
	v_mov_b32_e32 v18, v3
	v_mov_b32_e32 v17, v3
	v_mov_b32_e32 v16, v3
	v_mov_b32_e32 v23, v3
	v_mov_b32_e32 v22, v3
	v_mov_b32_e32 v21, v3
	v_mov_b32_e32 v20, v3
	v_mov_b32_e32 v43, v3
	v_mov_b32_e32 v42, v3
	v_mov_b32_e32 v41, v3
	v_mov_b32_e32 v40, v3
	v_mov_b32_e32 v47, v3
	v_mov_b32_e32 v46, v3
	v_mov_b32_e32 v45, v3
	s_waitcnt vmcnt(0)
	v_mov_b32_e32 v48, v234
	v_mov_b32_e32 v49, v235
	v_mov_b32_e32 v50, v236
	v_mov_b32_e32 v51, v237
	v_lshlrev_b32_e32 v44, 16, v48
	s_waitcnt lgkmcnt(1)
	v_sub_f32_e32 v44, v44, v52
	v_and_b32_e32 v48, 0xffff0000, v48
	v_mul_f32_e32 v44, v53, v44
	v_lshlrev_b32_e32 v54, 16, v49
	v_lshlrev_b32_e32 v55, 16, v50
	v_sub_f32_e32 v48, v48, v52
	v_fma_f32 v28, v36, v44, v28
	v_and_b32_e32 v49, 0xffff0000, v49
	v_and_b32_e32 v50, 0xffff0000, v50
	v_lshlrev_b32_e32 v56, 16, v51
	v_and_b32_e32 v51, 0xffff0000, v51
	v_sub_f32_e32 v54, v54, v52
	v_sub_f32_e32 v55, v55, v52
	v_mul_f32_e32 v48, v53, v48
	v_cvt_pk_bf16_f32 v28, v28, v79
	v_sub_f32_e32 v49, v49, v52
	v_sub_f32_e32 v50, v50, v52
	v_sub_f32_e32 v56, v56, v52
	v_sub_f32_e32 v51, v51, v52
	v_mul_f32_e32 v52, v53, v54
	v_mul_f32_e32 v54, v53, v55
	v_fma_f32 v29, v37, v48, v29
	ds_write_b16 v171, v28 offset:1024
	v_cvt_pk_bf16_f32 v28, v29, v79
	v_mul_f32_e32 v49, v53, v49
	v_fma_f32 v30, v38, v52, v30
	v_fma_f32 v24, v32, v54, v24
	ds_write_b16 v172, v28 offset:1024
	v_cvt_pk_bf16_f32 v28, v30, v79
	v_mul_f32_e32 v50, v53, v50
	v_fmac_f32_e32 v31, v39, v49
	ds_write_b16 v173, v28 offset:1024
	v_cvt_pk_bf16_f32 v28, v31, v79
	ds_write_b16 v174, v28 offset:1024
	v_cvt_pk_bf16_f32 v24, v24, v79
	v_mul_f32_e32 v55, v53, v56
	v_fma_f32 v25, v33, v50, v25
	ds_write_b16 v175, v24 offset:1024
	v_cvt_pk_bf16_f32 v24, v25, v79
	v_mul_f32_e32 v51, v53, v51
	v_fma_f32 v26, v34, v55, v26
	ds_write_b16 v176, v24 offset:1024
	v_cvt_pk_bf16_f32 v24, v26, v79
	v_mov_b32_e32 v44, v3
	v_fmac_f32_e32 v27, v35, v51
	ds_write_b16 v177, v24 offset:1024
	v_cvt_pk_bf16_f32 v24, v27, v79
	ds_write_b16 v178, v24 offset:1024
	s_lshl_b32 s90, s28, 7
	v_readlane_b32 s84, v254, 9
	v_readlane_b32 s85, v254, 10
	v_add_u32_e32 v242, s90, v96
	v_ashrrev_i32_e32 v243, 31, v242
	v_lshl_add_u64 v[242:243], v[242:243], 2, s[84:85]
	global_load_dword v246, v[242:243], off
	v_lshl_add_u64 v[242:243], s[0:1], 0, v[96:97]
	v_mov_b64_e32 v[244:245], s[34:35]
	v_mad_u64_u32 v[244:245], s[86:87], v242, s65, v[244:245]
	v_mov_b32_e32 v250, v245
	v_mad_u64_u32 v[250:251], s[86:87], v243, s65, v[250:251]
	v_mov_b32_e32 v245, v250
	v_or_b32_e32 v250, s90, v144
	v_lshlrev_b32_e32 v250, 1, v250
	v_mov_b32_e32 v251, 0
	v_lshl_add_u64 v[244:245], v[244:245], 0, v[250:251]
	global_load_dwordx2 v[248:249], v[244:245], off offset:1024
	global_load_dwordx2 v[226:227], v[244:245], off offset:1056
	global_load_dwordx2 v[228:229], v[244:245], off offset:1088
	global_load_dwordx2 v[230:231], v[244:245], off offset:1120
	global_load_dwordx2 v[232:233], v[244:245], off offset:1152
	global_load_dwordx2 v[234:235], v[244:245], off offset:1184
	global_load_dwordx2 v[236:237], v[244:245], off offset:1216
	global_load_dwordx2 v[240:241], v[244:245], off offset:1248
	s_waitcnt lgkmcnt(0)
	s_barrier
	s_cbranch_vccnz .LBB0_881
	s_and_b32 s6, s6, 0x1fffffe
	s_add_i32 s6, s6, s77
	s_and_b32 s6, s6, 3
	s_lshl_b32 s40, s6, 15
	v_mov_b32_e32 v44, 0
	v_lshl_add_u64 v[24:25], v[136:137], 0, s[40:41]
	v_mov_b32_e32 v26, v143
	s_mov_b32 s6, s64
	v_mov_b32_e32 v45, v44
	v_mov_b32_e32 v46, v44
	v_mov_b32_e32 v47, v44
	v_mov_b32_e32 v40, v44
	v_mov_b32_e32 v41, v44
	v_mov_b32_e32 v42, v44
	v_mov_b32_e32 v43, v44
	v_mov_b32_e32 v20, v44
	v_mov_b32_e32 v21, v44
	v_mov_b32_e32 v22, v44
	v_mov_b32_e32 v23, v44
	v_mov_b32_e32 v16, v44
	v_mov_b32_e32 v17, v44
	v_mov_b32_e32 v18, v44
	v_mov_b32_e32 v19, v44
	v_mov_b32_e32 v12, v44
	v_mov_b32_e32 v13, v44
	v_mov_b32_e32 v14, v44
	v_mov_b32_e32 v15, v44
	v_mov_b32_e32 v8, v44
	v_mov_b32_e32 v9, v44
	v_mov_b32_e32 v10, v44
	v_mov_b32_e32 v11, v44
	v_mov_b32_e32 v4, v44
	v_mov_b32_e32 v5, v44
	v_mov_b32_e32 v6, v44
	v_mov_b32_e32 v7, v44
	v_mov_b32_e32 v0, v44
	v_mov_b32_e32 v1, v44
	v_mov_b32_e32 v2, v44
	v_mov_b32_e32 v3, v44
